# P4 work split balanced with per-list staging cost padding; P3 item remap for balance; removed redundant cg grid sync at entry
# speedup vs baseline: 1.0244x; 1.0244x over previous
.LBB0_2:
	s_or_b64 exec, exec, s[20:21]
	s_load_dword s3, s[0:1], 0xb8
	s_waitcnt lgkmcnt(0)
	s_sub_i32 s4, s87, s86
	s_cmp_gt_i32 s4, 1
	s_cselect_b64 s[6:7], -1, 0
	s_cmp_lt_i32 s4, 2
	s_barrier
	s_cbranch_scc1 .LBB0_17
	v_mbcnt_lo_u32_b32 v0, -1, 0
	v_mbcnt_hi_u32_b32 v0, -1, v0
	s_and_b32 s4, s89, 0xffffffc0
	v_sub_u32_e32 v0, 0, v0
	s_barrier
	s_getreg_b32 s10, hwreg(HW_REG_XCC_ID, 0, 4)
	v_cmp_eq_u32_e32 vcc, s4, v0
	s_and_saveexec_b64 s[4:5], vcc
	s_cbranch_execz .LBB0_16
	s_mov_b64 s[8:9], exec
	v_mbcnt_lo_u32_b32 v0, s8, 0
	v_mbcnt_hi_u32_b32 v0, s9, v0
	v_cmp_eq_u32_e32 vcc, 0, v0
	s_and_b64 s[12:13], exec, vcc
	s_mov_b64 exec, s[12:13]
	s_cbranch_execz .LBB0_16
	s_load_dwordx2 s[0:1], s[0:1], 0xa8
	s_lshl_b32 s10, s10, 8
	s_and_b32 s10, s10, 0xf00
	v_mov_b32_e32 v0, 0x4000
	s_waitcnt lgkmcnt(0)
	s_add_u32 s0, s0, s10
	s_addc_u32 s1, s1, 0
	s_bcnt1_i32_b64 s8, s[8:9]
	v_mov_b32_e32 v1, s8
	global_atomic_add v0, v1, s[0:1] offset:1024

.LBB0_515:
	s_bfe_u32 s98, s51, 0x10008
	s_mul_i32 s98, s98, 63
	s_bfe_u32 s99, s51, 0x10009
	s_lshl_b32 s99, s99, 5
	s_xor_b32 s98, s98, s99
	s_xor_b32 s98, s51, s98
	s_and_b32 s52, s98, 63
	s_cmp_eq_u32 s52, 0
	s_cbranch_scc1 .LBB0_514
	s_ashr_i32 s6, s98, 6
	s_ashr_i32 s7, s6, 31
	s_lshl_b64 s[14:15], s[6:7], 15
	s_add_u32 s14, s26, s14
	s_addc_u32 s15, s27, s15
	v_lshl_add_u64 v[0:1], v[68:69], 2, s[14:15]
	v_lshl_add_u64 v[2:3], v[70:71], 2, s[14:15]
	v_lshl_add_u64 v[4:5], v[72:73], 2, s[14:15]
	v_lshl_add_u64 v[6:7], v[74:75], 2, s[14:15]
	global_load_dwordx2 v[8:9], v[0:1], off
	global_load_dwordx2 v[10:11], v[2:3], off
	global_load_dwordx2 v[12:13], v[4:5], off
	global_load_dwordx2 v[14:15], v[6:7], off
	v_lshl_add_u64 v[0:1], v[76:77], 2, s[14:15]
	v_lshl_add_u64 v[2:3], v[78:79], 2, s[14:15]
	v_lshl_add_u64 v[4:5], v[80:81], 2, s[14:15]
	v_lshl_add_u64 v[6:7], v[82:83], 2, s[14:15]
	global_load_dwordx2 v[16:17], v[0:1], off
	global_load_dwordx2 v[18:19], v[2:3], off
	global_load_dwordx2 v[20:21], v[4:5], off
	global_load_dwordx2 v[22:23], v[6:7], off
	s_lshl_b32 s7, s98, 5
	s_lshl_b32 s22, s52, 8
	s_lshl_b32 s6, s6, 8
	s_and_b32 s7, s7, 0xffffc000
	s_and_b32 s10, s6, 0x700
	s_or_b32 s6, s7, s22
	v_add_u32_e32 v0, s6, v86
	v_ashrrev_i32_e32 v1, 31, v0
	v_lshlrev_b64 v[0:1], 11, v[0:1]
	v_lshl_add_u64 v[0:1], s[12:13], 0, v[0:1]
	v_lshl_add_u64 v[0:1], v[0:1], 0, s[10:11]
	v_lshl_add_u64 v[0:1], v[0:1], 0, v[64:65]
	global_load_dwordx4 v[60:63], v[0:1], off
	global_load_dwordx4 v[56:59], v[0:1], off offset:32
	global_load_dwordx4 v[52:55], v[0:1], off offset:64
	global_load_dwordx4 v[48:51], v[0:1], off offset:96
	global_load_dwordx4 v[44:47], v[0:1], off offset:128
	global_load_dwordx4 v[40:43], v[0:1], off offset:160
	global_load_dwordx4 v[36:39], v[0:1], off offset:192
	global_load_dwordx4 v[32:35], v[0:1], off offset:224
	s_cmp_gt_u32 s52, 32
	s_cselect_b64 s[14:15], -1, 0
	s_cmp_lt_u32 s52, 33
	s_waitcnt vmcnt(0)
	v_cvt_pk_bf16_f32 v130, v8, v9
	v_cvt_pk_bf16_f32 v131, v10, v11
	v_cvt_pk_bf16_f32 v132, v12, v13
	v_cvt_pk_bf16_f32 v133, v14, v15
	v_lshlrev_b32_e32 v0, 16, v130
	v_cvt_pk_bf16_f32 v134, v16, v17
	v_cvt_pk_bf16_f32 v135, v18, v19
	v_cvt_pk_bf16_f32 v136, v20, v21
	v_cvt_pk_bf16_f32 v137, v22, v23
	v_and_b32_e32 v1, 0xffff0000, v130
	v_lshlrev_b32_e32 v2, 16, v131
	v_and_b32_e32 v3, 0xffff0000, v131
	v_lshlrev_b32_e32 v4, 16, v132
	v_and_b32_e32 v5, 0xffff0000, v132
	v_lshlrev_b32_e32 v6, 16, v133
	v_and_b32_e32 v7, 0xffff0000, v133
	v_lshlrev_b32_e32 v24, 16, v134
	v_and_b32_e32 v25, 0xffff0000, v134
	v_lshlrev_b32_e32 v26, 16, v135
	v_and_b32_e32 v27, 0xffff0000, v135
	v_lshlrev_b32_e32 v28, 16, v136
	v_and_b32_e32 v29, 0xffff0000, v136
	v_lshlrev_b32_e32 v30, 16, v137
	v_and_b32_e32 v31, 0xffff0000, v137
	v_pk_add_f32 v[0:1], v[8:9], v[0:1] neg_lo:[0,1] neg_hi:[0,1]
	v_pk_add_f32 v[2:3], v[10:11], v[2:3] neg_lo:[0,1] neg_hi:[0,1]
	v_pk_add_f32 v[4:5], v[12:13], v[4:5] neg_lo:[0,1] neg_hi:[0,1]
	v_pk_add_f32 v[6:7], v[14:15], v[6:7] neg_lo:[0,1] neg_hi:[0,1]
	v_pk_add_f32 v[8:9], v[16:17], v[24:25] neg_lo:[0,1] neg_hi:[0,1]
	v_pk_add_f32 v[10:11], v[18:19], v[26:27] neg_lo:[0,1] neg_hi:[0,1]
	v_pk_add_f32 v[12:13], v[20:21], v[28:29] neg_lo:[0,1] neg_hi:[0,1]
	v_pk_add_f32 v[14:15], v[22:23], v[30:31] neg_lo:[0,1] neg_hi:[0,1]
	v_cvt_pk_bf16_f32 v0, v0, v1
	v_cvt_pk_bf16_f32 v1, v2, v3
	v_cvt_pk_bf16_f32 v2, v4, v5
	v_cvt_pk_bf16_f32 v3, v6, v7
	v_cvt_pk_bf16_f32 v4, v8, v9
	v_cvt_pk_bf16_f32 v5, v10, v11
	v_cvt_pk_bf16_f32 v6, v12, v13
	v_cvt_pk_bf16_f32 v7, v14, v15
	ds_write2st64_b32 v120, v130, v0 offset1:68
	ds_write2st64_b32 v121, v131, v1 offset1:68
	ds_write2st64_b32 v122, v132, v2 offset1:68
	ds_write2st64_b32 v123, v133, v3 offset1:68
	ds_write2st64_b32 v124, v134, v4 offset1:68
	ds_write2st64_b32 v125, v135, v5 offset1:68
	ds_write2st64_b32 v126, v136, v6 offset1:68
	ds_write2st64_b32 v127, v137, v7 offset1:68
	s_waitcnt lgkmcnt(0)
	s_barrier
	ds_read_b128 v[0:3], v129
	ds_read_b128 v[4:7], v129 offset:32
	s_waitcnt lgkmcnt(1)
	v_mfma_f32_32x32x16_bf16 v[16:31], v[0:3], v[60:63], 0
	ds_read_b128 v[0:3], v129 offset:17408
	ds_read_b128 v[8:11], v129 offset:17440
	v_mov_b32_e32 v12, 0
	v_mov_b32_e32 v13, 0
	v_mov_b32_e32 v14, 0
	v_mov_b32_e32 v15, 0
	s_waitcnt lgkmcnt(1)
	v_mfma_f32_32x32x16_bf16 v[16:31], v[0:3], v[60:63], v[16:31]
	v_mfma_f32_32x32x16_bf16 v[16:31], v[4:7], v[56:59], v[16:31]
	ds_read_b128 v[0:3], v129 offset:64
	ds_read_b128 v[4:7], v129 offset:96
	s_waitcnt lgkmcnt(2)
	v_mfma_f32_32x32x16_bf16 v[16:31], v[8:11], v[56:59], v[16:31]
	s_waitcnt lgkmcnt(1)
	v_mfma_f32_32x32x16_bf16 v[16:31], v[0:3], v[52:55], v[16:31]
	ds_read_b128 v[0:3], v129 offset:17472
	ds_read_b128 v[8:11], v129 offset:17504
	s_waitcnt lgkmcnt(1)
	v_mfma_f32_32x32x16_bf16 v[16:31], v[0:3], v[52:55], v[16:31]
	v_mfma_f32_32x32x16_bf16 v[16:31], v[4:7], v[48:51], v[16:31]
	ds_read_b128 v[0:3], v129 offset:128
	ds_read_b128 v[4:7], v129 offset:160
	s_waitcnt lgkmcnt(2)
	v_mfma_f32_32x32x16_bf16 v[16:31], v[8:11], v[48:51], v[16:31]
	s_waitcnt lgkmcnt(1)
	v_mfma_f32_32x32x16_bf16 v[16:31], v[0:3], v[44:47], v[16:31]
	ds_read_b128 v[0:3], v129 offset:17536
	ds_read_b128 v[8:11], v129 offset:17568
	s_waitcnt lgkmcnt(1)
	v_mfma_f32_32x32x16_bf16 v[16:31], v[0:3], v[44:47], v[16:31]
	v_mfma_f32_32x32x16_bf16 v[16:31], v[4:7], v[40:43], v[16:31]
	ds_read_b128 v[0:3], v129 offset:192
	ds_read_b128 v[4:7], v129 offset:224
	s_waitcnt lgkmcnt(2)
	v_mfma_f32_32x32x16_bf16 v[16:31], v[8:11], v[40:43], v[16:31]
	s_waitcnt lgkmcnt(1)
	v_mfma_f32_32x32x16_bf16 v[16:31], v[0:3], v[36:39], v[16:31]
	ds_read_b128 v[0:3], v129 offset:17600
	ds_read_b128 v[8:11], v129 offset:17632
	s_waitcnt lgkmcnt(1)
	v_mfma_f32_32x32x16_bf16 v[16:31], v[0:3], v[36:39], v[16:31]
	v_mov_b32_e32 v0, 0
	v_mov_b32_e32 v1, 0
	v_mov_b32_e32 v2, 0
	v_mov_b32_e32 v3, 0
	v_mfma_f32_32x32x16_bf16 v[16:31], v[4:7], v[32:35], v[16:31]
	v_mov_b32_e32 v4, 0
	v_mov_b32_e32 v5, 0
	v_mov_b32_e32 v6, 0
	v_mov_b32_e32 v7, 0
	s_waitcnt lgkmcnt(0)
	v_mfma_f32_32x32x16_bf16 v[16:31], v[8:11], v[32:35], v[16:31]
	v_mov_b32_e32 v8, 0
	v_mov_b32_e32 v9, 0
	v_mov_b32_e32 v10, 0
	v_mov_b32_e32 v11, 0
	s_cbranch_scc1 .LBB0_518
	ds_read_b128 v[0:3], v129 offset:8704
	ds_read_b128 v[130:133], v129 offset:8736
	ds_read_b128 v[134:137], v129 offset:26112
	ds_read_b128 v[138:141], v129 offset:26144
	s_waitcnt lgkmcnt(3)
	v_mfma_f32_32x32x16_bf16 v[0:15], v[0:3], v[60:63], 0
	s_waitcnt lgkmcnt(1)
	v_mfma_f32_32x32x16_bf16 v[0:15], v[134:137], v[60:63], v[0:15]
	v_mfma_f32_32x32x16_bf16 v[0:15], v[130:133], v[56:59], v[0:15]
	s_waitcnt lgkmcnt(0)
	v_mfma_f32_32x32x16_bf16 v[0:15], v[138:141], v[56:59], v[0:15]
	ds_read_b128 v[56:59], v129 offset:8768
	ds_read_b128 v[60:63], v129 offset:8800
	s_waitcnt lgkmcnt(1)
	v_mfma_f32_32x32x16_bf16 v[0:15], v[56:59], v[52:55], v[0:15]
	ds_read_b128 v[56:59], v129 offset:26176
	ds_read_b128 v[130:133], v129 offset:26208
	s_waitcnt lgkmcnt(1)
	v_mfma_f32_32x32x16_bf16 v[0:15], v[56:59], v[52:55], v[0:15]
	v_mfma_f32_32x32x16_bf16 v[0:15], v[60:63], v[48:51], v[0:15]
	s_waitcnt lgkmcnt(0)
	v_mfma_f32_32x32x16_bf16 v[0:15], v[130:133], v[48:51], v[0:15]
	ds_read_b128 v[48:51], v129 offset:8832
	ds_read_b128 v[52:55], v129 offset:8864
	s_waitcnt lgkmcnt(1)
	v_mfma_f32_32x32x16_bf16 v[0:15], v[48:51], v[44:47], v[0:15]
	ds_read_b128 v[48:51], v129 offset:26240
	ds_read_b128 v[56:59], v129 offset:26272
	s_waitcnt lgkmcnt(1)
	v_mfma_f32_32x32x16_bf16 v[0:15], v[48:51], v[44:47], v[0:15]
	v_mfma_f32_32x32x16_bf16 v[0:15], v[52:55], v[40:43], v[0:15]
	s_waitcnt lgkmcnt(0)
	v_mfma_f32_32x32x16_bf16 v[0:15], v[56:59], v[40:43], v[0:15]
	ds_read_b128 v[40:43], v129 offset:8896
	ds_read_b128 v[44:47], v129 offset:8928
	s_waitcnt lgkmcnt(1)
	v_mfma_f32_32x32x16_bf16 v[0:15], v[40:43], v[36:39], v[0:15]
	ds_read_b128 v[40:43], v129 offset:26304
	ds_read_b128 v[48:51], v129 offset:26336
	s_waitcnt lgkmcnt(1)
	v_mfma_f32_32x32x16_bf16 v[0:15], v[40:43], v[36:39], v[0:15]
	v_mfma_f32_32x32x16_bf16 v[0:15], v[44:47], v[32:35], v[0:15]
	s_waitcnt lgkmcnt(0)
	v_mfma_f32_32x32x16_bf16 v[0:15], v[48:51], v[32:35], v[0:15]

.LBB0_647:
	s_or_b64 exec, exec, s[6:7]
	s_cmp_ge_u32 s73, s52
	s_waitcnt lgkmcnt(0)
	s_barrier
	s_cbranch_scc1 .LBB0_513
	ds_read_u8 v1, v85 offset:35328
	ds_read_u8 v2, v85 offset:35392
	ds_read_u8 v3, v85 offset:35456
	ds_read_u8 v4, v85 offset:35520
	ds_read_u8 v13, v85 offset:34880
	ds_read_u8 v14, v85 offset:34944
	ds_read_u8 v15, v85 offset:35008
	ds_read_u8 v16, v85 offset:35072
	ds_read_u8 v17, v85 offset:35136
	ds_read_u8 v18, v85 offset:35200
	ds_read_u8 v19, v85 offset:35264
	ds_read_u8 v20, v85 offset:34816
	v_add_u32_e32 v0, s22, v84
	v_add_u32_e32 v5, 64, v0
	v_add_u32_e32 v6, 0x80, v0
	v_add_u32_e32 v7, 0xc0, v0
	s_and_b32 s53, s98, 0xffffffc0
	v_or_b32_e32 v8, 0x4000, v0
	v_or_b32_e32 v9, 0x4000, v5
	v_or_b32_e32 v10, 0x4000, v6
	v_or_b32_e32 v11, 0x4000, v7
	v_or_b32_e32 v12, 0x8000, v0
	v_or_b32_e32 v21, 0x8000, v5
	v_or_b32_e32 v22, 0x8000, v6
	v_or_b32_e32 v23, 0x8000, v7
	s_mov_b32 s54, s73
	s_branch .LBB0_651

.LBB0_771:
	s_cmp_lt_i32 s74, 5
	s_cselect_b64 s[4:5], -1, 0
	s_and_b64 s[6:7], s[4:5], s[0:1]
	s_andn2_b64 vcc, exec, s[6:7]
	s_cbranch_vccnz .LBB0_882
	v_mbcnt_lo_u32_b32 v0, -1, 0
	s_add_i32 s0, 0, 0x250a8
	v_mbcnt_hi_u32_b32 v3, -1, v0
	v_mov_b32_e32 v0, s0
	ds_read_b64 v[4:5], v0
	s_and_b32 s0, s78, 0xffffffc0
	v_add_u32_e32 v2, s0, v3
	v_lshlrev_b32_e32 v0, 1, v2
	v_ashrrev_i32_e32 v1, 31, v0
	s_waitcnt lgkmcnt(0)
	v_readfirstlane_b32 s29, v5
	v_readfirstlane_b32 s28, v4
	v_add_u32_e32 v7, -2, v3
	v_add_u32_e32 v8, -4, v3
	v_lshl_add_u64 v[4:5], v[0:1], 2, s[28:29]
	global_load_dword v1, v[4:5], off sc1
	global_load_dword v6, v[4:5], off offset:4 sc1
	v_and_b32_e32 v4, 64, v3
	v_add_u32_e32 v5, -1, v3
	v_cmp_lt_i32_e32 vcc, v5, v4
	v_add_u32_e32 v9, -8, v3
	v_add_u32_e32 v10, -16, v3
	v_cndmask_b32_e32 v5, v5, v3, vcc
	v_lshlrev_b32_e32 v5, 2, v5
	v_cmp_lt_i32_e32 vcc, v7, v4
	v_cmp_lt_i32_e64 s[4:5], 31, v3
	s_waitcnt vmcnt(0)
	v_add_u32_e32 v1, 31, v1
	v_add_u32_e32 v6, 31, v6
	v_lshrrev_b32_e32 v11, 5, v1
	v_lshrrev_b32_e32 v1, 5, v6
	v_min_u32_e32 v12, 1, v11
	v_add_u32_e32 v13, 7, v11
	v_and_b32_e32 v13, -8, v13
	v_mad_u32_u24 v11, v12, 8, v13
	v_min_u32_e32 v12, 1, v1
	v_add_u32_e32 v13, 7, v1
	v_and_b32_e32 v13, -8, v13
	v_mad_u32_u24 v1, v12, 8, v13
	v_add_u32_e32 v6, v1, v11
	ds_bpermute_b32 v5, v5, v6
	v_cndmask_b32_e32 v7, v7, v3, vcc
	v_cmp_lt_i32_e32 vcc, 0, v3
	v_lshlrev_b32_e32 v7, 2, v7
	s_waitcnt lgkmcnt(0)
	v_cndmask_b32_e32 v5, 0, v5, vcc
	v_add_u32_e32 v5, v5, v6
	ds_bpermute_b32 v6, v7, v5
	v_cmp_lt_i32_e32 vcc, v8, v4
	s_nop 1
	v_cndmask_b32_e32 v7, v8, v3, vcc
	v_cmp_lt_i32_e32 vcc, 1, v3
	v_lshlrev_b32_e32 v7, 2, v7
	s_waitcnt lgkmcnt(0)
	v_cndmask_b32_e32 v6, 0, v6, vcc
	v_add_u32_e32 v5, v6, v5
	ds_bpermute_b32 v6, v7, v5
	v_cmp_lt_i32_e32 vcc, v9, v4
	s_nop 1
	v_cndmask_b32_e32 v7, v9, v3, vcc
	v_cmp_lt_i32_e32 vcc, 3, v3
	v_lshlrev_b32_e32 v7, 2, v7
	s_waitcnt lgkmcnt(0)
	v_cndmask_b32_e32 v6, 0, v6, vcc
	v_add_u32_e32 v5, v6, v5
	ds_bpermute_b32 v6, v7, v5
	v_cmp_lt_i32_e32 vcc, v10, v4
	s_nop 1
	v_cndmask_b32_e32 v7, v10, v3, vcc
	v_cmp_lt_i32_e32 vcc, 7, v3
	v_lshlrev_b32_e32 v7, 2, v7
	s_waitcnt lgkmcnt(0)
	v_cndmask_b32_e32 v6, 0, v6, vcc
	v_add_u32_e32 v5, v6, v5
	ds_bpermute_b32 v6, v7, v5
	v_subrev_co_u32_e64 v7, s[0:1], 32, v3
	v_cmp_lt_i32_e32 vcc, v7, v4
	s_nop 1
	v_cndmask_b32_e32 v4, v7, v3, vcc
	v_cmp_lt_i32_e32 vcc, 15, v3
	v_lshlrev_b32_e32 v4, 2, v4
	s_waitcnt lgkmcnt(0)
	v_cndmask_b32_e32 v6, 0, v6, vcc
	v_add_u32_e32 v5, v6, v5
	ds_bpermute_b32 v4, v4, v5
	v_cmp_eq_u32_e32 vcc, 63, v3
	s_waitcnt lgkmcnt(0)
	v_cndmask_b32_e64 v4, 0, v4, s[4:5]
	v_add_u32_e32 v8, v4, v5
	s_and_saveexec_b64 s[4:5], vcc
	s_lshl_b32 s8, s73, 2
	s_add_i32 s8, s8, 0
	s_add_i32 s8, s8, 0x23800
	v_mov_b32_e32 v4, s8
	ds_write_b32 v4, v8
	s_or_b64 exec, exec, s[4:5]
	s_cmp_lt_u32 s78, 64
	v_mov_b32_e32 v4, 0
	s_waitcnt lgkmcnt(0)
	s_barrier
	s_cbranch_scc1 .LBB0_787
	s_cmpk_lt_u32 s78, 0x100
	s_cbranch_scc1 .LBB0_780
	s_add_i32 s9, s73, -4
	s_lshr_b32 s8, s9, 2
	s_add_i32 s8, s8, 1
	s_mov_b32 s4, 0
	s_cmp_lt_u32 s9, 28
	s_cbranch_scc1 .LBB0_781
	s_add_i32 s5, 0, 0x23800
	s_and_b32 s9, s8, 0x7ffffff8
	v_mov_b32_e32 v7, 0
	v_mov_b32_e32 v6, 0
	v_mov_b32_e32 v5, 0
	v_mov_b32_e32 v4, 0

.LBB0_797:
	s_min_u32 s4, s62, s30
	s_cmp_ge_u32 s62, s30
	s_mov_b32 s5, s58
	s_cbranch_scc1 .LBB0_882

.LBB0_802:
	v_mov_b32_e32 v0, s55
	s_waitcnt lgkmcnt(0)
	s_barrier
	ds_read_b32 v197, v0
	s_min_u32 s65, s62, s30
	s_add_i32 s98, s64, 31
	s_lshr_b32 s98, s98, 5
	s_add_i32 s98, s98, s63
	s_min_u32 s65, s65, s98
	s_add_i32 s66, s4, s73
	s_cmp_lt_u32 s66, s65
	v_mov_b32_e32 v198, 0x3fff
	s_mov_b64 s[10:11], 0
	s_cselect_b64 s[14:15], -1, 0
	s_cmp_ge_u32 s66, s65
	s_mov_b64 s[12:13], 0
	v_mov_b32_e32 v200, 0x3fff
	s_cbranch_scc1 .LBB0_806
	s_sub_i32 s4, s66, s63
	v_lshl_or_b32 v2, s4, 5, v181
	v_cmp_gt_i32_e32 vcc, s64, v2
	v_mov_b32_e32 v200, 0x3fff
	s_and_saveexec_b64 s[4:5], vcc
	s_cbranch_execz .LBB0_805
	s_lshl_b64 s[16:17], s[34:35], 16
	s_add_u32 s16, s33, s16
	s_addc_u32 s17, s42, s17
	v_ashrrev_i32_e32 v3, 31, v2
	v_lshl_add_u64 v[2:3], v[2:3], 2, s[16:17]
	global_load_dword v200, v[2:3], off sc1
	s_mov_b64 s[12:13], exec

	.amdhsa_kernel _Z3fwd4Args
		.amdhsa_group_segment_fixed_size 0
		.amdhsa_private_segment_fixed_size 0
		.amdhsa_kernarg_size 440
		.amdhsa_user_sgpr_count 2
		.amdhsa_user_sgpr_dispatch_ptr 0
		.amdhsa_user_sgpr_queue_ptr 0
		.amdhsa_user_sgpr_kernarg_segment_ptr 1
		.amdhsa_user_sgpr_dispatch_id 0
		.amdhsa_user_sgpr_kernarg_preload_length 0
		.amdhsa_user_sgpr_kernarg_preload_offset 0
		.amdhsa_user_sgpr_private_segment_size 0
		.amdhsa_uses_dynamic_stack 0
		.amdhsa_enable_private_segment 0
		.amdhsa_system_sgpr_workgroup_id_x 1
		.amdhsa_system_sgpr_workgroup_id_y 0
		.amdhsa_system_sgpr_workgroup_id_z 0
		.amdhsa_system_sgpr_workgroup_info 0
		.amdhsa_system_vgpr_workitem_id 2
		.amdhsa_next_free_vgpr 255
		.amdhsa_next_free_sgpr 102
		.amdhsa_accum_offset 256
		.amdhsa_reserve_vcc 1
		.amdhsa_float_round_mode_32 0
		.amdhsa_float_round_mode_16_64 0
		.amdhsa_float_denorm_mode_32 3
		.amdhsa_float_denorm_mode_16_64 3
		.amdhsa_dx10_clamp 1
		.amdhsa_ieee_mode 1
		.amdhsa_fp16_overflow 0
		.amdhsa_tg_split 0
		.amdhsa_exception_fp_ieee_invalid_op 0
		.amdhsa_exception_fp_denorm_src 0
		.amdhsa_exception_fp_ieee_div_zero 0
		.amdhsa_exception_fp_ieee_overflow 0
		.amdhsa_exception_fp_ieee_underflow 0
		.amdhsa_exception_fp_ieee_inexact 0
		.amdhsa_exception_int_div_zero 0
	.end_amdhsa_kernel

amdhsa.kernels:
  - .agpr_count:     0
    .args:
      - .offset:         0
        .size:           184
        .value_kind:     by_value
      - .offset:         184
        .size:           4
        .value_kind:     hidden_block_count_x
      - .offset:         188
        .size:           4
        .value_kind:     hidden_block_count_y
      - .offset:         192
        .size:           4
        .value_kind:     hidden_block_count_z
      - .offset:         196
        .size:           2
        .value_kind:     hidden_group_size_x
      - .offset:         198
        .size:           2
        .value_kind:     hidden_group_size_y
      - .offset:         200
        .size:           2
        .value_kind:     hidden_group_size_z
      - .offset:         202
        .size:           2
        .value_kind:     hidden_remainder_x
      - .offset:         204
        .size:           2
        .value_kind:     hidden_remainder_y
      - .offset:         206
        .size:           2
        .value_kind:     hidden_remainder_z
      - .offset:         224
        .size:           8
        .value_kind:     hidden_global_offset_x
      - .offset:         232
        .size:           8
        .value_kind:     hidden_global_offset_y
      - .offset:         240
        .size:           8
        .value_kind:     hidden_global_offset_z
      - .offset:         248
        .size:           2
        .value_kind:     hidden_grid_dims
      - .offset:         272
        .size:           8
        .value_kind:     hidden_multigrid_sync_arg
      - .offset:         304
        .size:           4
        .value_kind:     hidden_dynamic_lds_size
    .group_segment_fixed_size: 0
    .kernarg_segment_align: 8
    .kernarg_segment_size: 440
    .language:       OpenCL C
    .language_version:
      - 2
      - 0
    .max_flat_workgroup_size: 512
    .name:           _Z3fwd4Args
    .private_segment_fixed_size: 0
    .sgpr_count:     108
    .sgpr_spill_count: 8
    .symbol:         _Z3fwd4Args.kd
    .uniform_work_group_size: 1
    .uses_dynamic_stack: false
    .vgpr_count:     255
    .vgpr_spill_count: 0
    .wavefront_size: 64
